# nt hint also on the gated-residual epilogues' residual reads and on the modulated norms' row loads
# speedup vs baseline: 1.0061x; 1.0061x over previous
.Lnm_n1_loop:
	s_ashr_i32 s11, s10, 31
	s_lshl_b64 s[0:1], s[10:11], 13
	v_lshl_add_u64 v[110:111], v[82:83], 0, s[0:1]
	global_load_dwordx4 v[4:7], v[110:111], off nt
	s_add_u32 s0, s0, 0x2000
	s_addc_u32 s1, s1, 0
	v_lshl_add_u64 v[110:111], v[82:83], 0, s[0:1]
	global_load_dwordx4 v[8:11], v[110:111], off nt
	s_add_u32 s0, s0, 0x2000
	s_addc_u32 s1, s1, 0
	v_lshl_add_u64 v[110:111], v[82:83], 0, s[0:1]
	global_load_dwordx4 v[12:15], v[110:111], off nt
	s_add_u32 s0, s0, 0x2000
	s_addc_u32 s1, s1, 0
	v_lshl_add_u64 v[110:111], v[82:83], 0, s[0:1]
	global_load_dwordx4 v[16:19], v[110:111], off nt
	s_add_u32 s0, s0, 0x2000
	s_addc_u32 s1, s1, 0
	v_lshl_add_u64 v[110:111], v[82:83], 0, s[0:1]
	global_load_dwordx4 v[20:23], v[110:111], off nt
	s_add_u32 s0, s0, 0x2000
	s_addc_u32 s1, s1, 0
	v_lshl_add_u64 v[110:111], v[82:83], 0, s[0:1]
	global_load_dwordx4 v[24:27], v[110:111], off nt
	s_add_u32 s0, s0, 0x2000
	s_addc_u32 s1, s1, 0
	v_lshl_add_u64 v[110:111], v[82:83], 0, s[0:1]
	global_load_dwordx4 v[28:31], v[110:111], off nt
	s_add_u32 s0, s0, 0x2000
	s_addc_u32 s1, s1, 0
	v_lshl_add_u64 v[110:111], v[82:83], 0, s[0:1]
	global_load_dwordx4 v[32:35], v[110:111], off nt
	s_add_u32 s0, s0, 0x2000
	s_addc_u32 s1, s1, 0
	v_lshl_add_u64 v[110:111], v[82:83], 0, s[0:1]
	global_load_dwordx4 v[36:39], v[110:111], off nt
	s_add_u32 s0, s0, 0x2000
	s_addc_u32 s1, s1, 0
	v_lshl_add_u64 v[110:111], v[82:83], 0, s[0:1]
	global_load_dwordx4 v[40:43], v[110:111], off nt
	s_add_u32 s0, s0, 0x2000
	s_addc_u32 s1, s1, 0
	v_lshl_add_u64 v[110:111], v[82:83], 0, s[0:1]
	global_load_dwordx4 v[44:47], v[110:111], off nt
	s_add_u32 s0, s0, 0x2000
	s_addc_u32 s1, s1, 0
	v_lshl_add_u64 v[110:111], v[82:83], 0, s[0:1]
	global_load_dwordx4 v[48:51], v[110:111], off nt
	s_add_u32 s0, s0, 0x2000
	s_addc_u32 s1, s1, 0
	v_lshl_add_u64 v[110:111], v[82:83], 0, s[0:1]
	global_load_dwordx4 v[52:55], v[110:111], off nt
	s_add_u32 s0, s0, 0x2000
	s_addc_u32 s1, s1, 0
	v_lshl_add_u64 v[110:111], v[82:83], 0, s[0:1]
	global_load_dwordx4 v[56:59], v[110:111], off nt
	s_add_u32 s0, s0, 0x2000
	s_addc_u32 s1, s1, 0
	v_lshl_add_u64 v[110:111], v[82:83], 0, s[0:1]
	global_load_dwordx4 v[60:63], v[110:111], off nt
	s_add_u32 s0, s0, 0x2000
	s_addc_u32 s1, s1, 0
	v_lshl_add_u64 v[110:111], v[82:83], 0, s[0:1]
	global_load_dwordx4 v[64:67], v[110:111], off nt
	s_ashr_i32 s0, s22, 8
	v_mad_i64_i32 v[110:111], s[0:1], s0, v178, v[80:81]
	v_lshl_add_u64 v[112:113], v[110:111], 0, s[12:13]
	global_load_dwordx4 v[118:121], v[112:113], off
	s_mov_b32 s0, 0x0
	s_mov_b32 s1, 0
	v_lshl_add_u64 v[112:113], v[110:111], 0, s[0:1]
	global_load_dwordx4 v[250:253], v[112:113], off
	s_waitcnt vmcnt(17)
	v_mul_f32_e32 v68, v5, v5
	v_mul_f32_e32 v102, v7, v7
	v_fmac_f32_e32 v68, v4, v4
	v_fmac_f32_e32 v102, v6, v6
	v_add_f32_e32 v68, v68, v102
	s_waitcnt vmcnt(16)
	v_mul_f32_e32 v69, v9, v9
	v_mul_f32_e32 v103, v11, v11
	v_fmac_f32_e32 v69, v8, v8
	v_fmac_f32_e32 v103, v10, v10
	v_add_f32_e32 v69, v69, v103
	s_waitcnt vmcnt(15)
	v_mul_f32_e32 v70, v13, v13
	v_mul_f32_e32 v104, v15, v15
	v_fmac_f32_e32 v70, v12, v12
	v_fmac_f32_e32 v104, v14, v14
	v_add_f32_e32 v70, v70, v104
	s_waitcnt vmcnt(14)
	v_mul_f32_e32 v71, v17, v17
	v_mul_f32_e32 v105, v19, v19
	v_fmac_f32_e32 v71, v16, v16
	v_fmac_f32_e32 v105, v18, v18
	v_add_f32_e32 v71, v71, v105
	s_waitcnt vmcnt(13)
	v_mul_f32_e32 v72, v21, v21
	v_mul_f32_e32 v106, v23, v23
	v_fmac_f32_e32 v72, v20, v20
	v_fmac_f32_e32 v106, v22, v22
	v_add_f32_e32 v72, v72, v106
	s_waitcnt vmcnt(12)
	v_mul_f32_e32 v73, v25, v25
	v_mul_f32_e32 v107, v27, v27
	v_fmac_f32_e32 v73, v24, v24
	v_fmac_f32_e32 v107, v26, v26
	v_add_f32_e32 v73, v73, v107
	s_waitcnt vmcnt(11)
	v_mul_f32_e32 v74, v29, v29
	v_mul_f32_e32 v108, v31, v31
	v_fmac_f32_e32 v74, v28, v28
	v_fmac_f32_e32 v108, v30, v30
	v_add_f32_e32 v74, v74, v108
	s_waitcnt vmcnt(10)
	v_mul_f32_e32 v75, v33, v33
	v_mul_f32_e32 v109, v35, v35
	v_fmac_f32_e32 v75, v32, v32
	v_fmac_f32_e32 v109, v34, v34
	v_add_f32_e32 v75, v75, v109
	s_waitcnt vmcnt(9)
	v_mul_f32_e32 v94, v37, v37
	v_mul_f32_e32 v110, v39, v39
	v_fmac_f32_e32 v94, v36, v36
	v_fmac_f32_e32 v110, v38, v38
	v_add_f32_e32 v94, v94, v110
	s_waitcnt vmcnt(8)
	v_mul_f32_e32 v95, v41, v41
	v_mul_f32_e32 v111, v43, v43
	v_fmac_f32_e32 v95, v40, v40
	v_fmac_f32_e32 v111, v42, v42
	v_add_f32_e32 v95, v95, v111
	s_waitcnt vmcnt(7)
	v_mul_f32_e32 v96, v45, v45
	v_mul_f32_e32 v112, v47, v47
	v_fmac_f32_e32 v96, v44, v44
	v_fmac_f32_e32 v112, v46, v46
	v_add_f32_e32 v96, v96, v112
	s_waitcnt vmcnt(6)
	v_mul_f32_e32 v97, v49, v49
	v_mul_f32_e32 v113, v51, v51
	v_fmac_f32_e32 v97, v48, v48
	v_fmac_f32_e32 v113, v50, v50
	v_add_f32_e32 v97, v97, v113
	s_waitcnt vmcnt(5)
	v_mul_f32_e32 v98, v53, v53
	v_mul_f32_e32 v114, v55, v55
	v_fmac_f32_e32 v98, v52, v52
	v_fmac_f32_e32 v114, v54, v54
	v_add_f32_e32 v98, v98, v114
	s_waitcnt vmcnt(4)
	v_mul_f32_e32 v99, v57, v57
	v_mul_f32_e32 v115, v59, v59
	v_fmac_f32_e32 v99, v56, v56
	v_fmac_f32_e32 v115, v58, v58
	v_add_f32_e32 v99, v99, v115
	s_waitcnt vmcnt(3)
	v_mul_f32_e32 v100, v61, v61
	v_mul_f32_e32 v116, v63, v63
	v_fmac_f32_e32 v100, v60, v60
	v_fmac_f32_e32 v116, v62, v62
	v_add_f32_e32 v100, v100, v116
	s_waitcnt vmcnt(2)
	v_mul_f32_e32 v101, v65, v65
	v_mul_f32_e32 v117, v67, v67
	v_fmac_f32_e32 v101, v64, v64
	v_fmac_f32_e32 v117, v66, v66
	v_add_f32_e32 v101, v101, v117
	ds_bpermute_b32 v102, v85, v68
	ds_bpermute_b32 v103, v85, v69
	ds_bpermute_b32 v104, v85, v70
	ds_bpermute_b32 v105, v85, v71
	ds_bpermute_b32 v106, v85, v72
	ds_bpermute_b32 v107, v85, v73
	ds_bpermute_b32 v108, v85, v74
	ds_bpermute_b32 v109, v85, v75
	ds_bpermute_b32 v110, v85, v94
	ds_bpermute_b32 v111, v85, v95
	ds_bpermute_b32 v112, v85, v96
	ds_bpermute_b32 v113, v85, v97
	ds_bpermute_b32 v114, v85, v98
	ds_bpermute_b32 v115, v85, v99
	ds_bpermute_b32 v116, v85, v100
	ds_bpermute_b32 v117, v85, v101
	s_waitcnt lgkmcnt(15)
	v_add_f32_e32 v68, v68, v102
	s_waitcnt lgkmcnt(14)
	v_add_f32_e32 v69, v69, v103
	s_waitcnt lgkmcnt(13)
	v_add_f32_e32 v70, v70, v104
	s_waitcnt lgkmcnt(12)
	v_add_f32_e32 v71, v71, v105
	s_waitcnt lgkmcnt(11)
	v_add_f32_e32 v72, v72, v106
	s_waitcnt lgkmcnt(10)
	v_add_f32_e32 v73, v73, v107
	s_waitcnt lgkmcnt(9)
	v_add_f32_e32 v74, v74, v108
	s_waitcnt lgkmcnt(8)
	v_add_f32_e32 v75, v75, v109
	s_waitcnt lgkmcnt(7)
	v_add_f32_e32 v94, v94, v110
	s_waitcnt lgkmcnt(6)
	v_add_f32_e32 v95, v95, v111
	s_waitcnt lgkmcnt(5)
	v_add_f32_e32 v96, v96, v112
	s_waitcnt lgkmcnt(4)
	v_add_f32_e32 v97, v97, v113
	s_waitcnt lgkmcnt(3)
	v_add_f32_e32 v98, v98, v114
	s_waitcnt lgkmcnt(2)
	v_add_f32_e32 v99, v99, v115
	s_waitcnt lgkmcnt(1)
	v_add_f32_e32 v100, v100, v116
	s_waitcnt lgkmcnt(0)
	v_add_f32_e32 v101, v101, v117
	ds_bpermute_b32 v102, v86, v68
	ds_bpermute_b32 v103, v86, v69
	ds_bpermute_b32 v104, v86, v70
	ds_bpermute_b32 v105, v86, v71
	ds_bpermute_b32 v106, v86, v72
	ds_bpermute_b32 v107, v86, v73
	ds_bpermute_b32 v108, v86, v74
	ds_bpermute_b32 v109, v86, v75
	ds_bpermute_b32 v110, v86, v94
	ds_bpermute_b32 v111, v86, v95
	ds_bpermute_b32 v112, v86, v96
	ds_bpermute_b32 v113, v86, v97
	ds_bpermute_b32 v114, v86, v98
	ds_bpermute_b32 v115, v86, v99
	ds_bpermute_b32 v116, v86, v100
	ds_bpermute_b32 v117, v86, v101
	s_waitcnt lgkmcnt(15)
	v_add_f32_e32 v68, v68, v102
	s_waitcnt lgkmcnt(14)
	v_add_f32_e32 v69, v69, v103
	s_waitcnt lgkmcnt(13)
	v_add_f32_e32 v70, v70, v104
	s_waitcnt lgkmcnt(12)
	v_add_f32_e32 v71, v71, v105
	s_waitcnt lgkmcnt(11)
	v_add_f32_e32 v72, v72, v106
	s_waitcnt lgkmcnt(10)
	v_add_f32_e32 v73, v73, v107
	s_waitcnt lgkmcnt(9)
	v_add_f32_e32 v74, v74, v108
	s_waitcnt lgkmcnt(8)
	v_add_f32_e32 v75, v75, v109
	s_waitcnt lgkmcnt(7)
	v_add_f32_e32 v94, v94, v110
	s_waitcnt lgkmcnt(6)
	v_add_f32_e32 v95, v95, v111
	s_waitcnt lgkmcnt(5)
	v_add_f32_e32 v96, v96, v112
	s_waitcnt lgkmcnt(4)
	v_add_f32_e32 v97, v97, v113
	s_waitcnt lgkmcnt(3)
	v_add_f32_e32 v98, v98, v114
	s_waitcnt lgkmcnt(2)
	v_add_f32_e32 v99, v99, v115
	s_waitcnt lgkmcnt(1)
	v_add_f32_e32 v100, v100, v116
	s_waitcnt lgkmcnt(0)
	v_add_f32_e32 v101, v101, v117
	ds_bpermute_b32 v102, v87, v68
	ds_bpermute_b32 v103, v87, v69
	ds_bpermute_b32 v104, v87, v70
	ds_bpermute_b32 v105, v87, v71
	ds_bpermute_b32 v106, v87, v72
	ds_bpermute_b32 v107, v87, v73
	ds_bpermute_b32 v108, v87, v74
	ds_bpermute_b32 v109, v87, v75
	ds_bpermute_b32 v110, v87, v94
	ds_bpermute_b32 v111, v87, v95
	ds_bpermute_b32 v112, v87, v96
	ds_bpermute_b32 v113, v87, v97
	ds_bpermute_b32 v114, v87, v98
	ds_bpermute_b32 v115, v87, v99
	ds_bpermute_b32 v116, v87, v100
	ds_bpermute_b32 v117, v87, v101
	s_waitcnt lgkmcnt(15)
	v_add_f32_e32 v68, v68, v102
	s_waitcnt lgkmcnt(14)
	v_add_f32_e32 v69, v69, v103
	s_waitcnt lgkmcnt(13)
	v_add_f32_e32 v70, v70, v104
	s_waitcnt lgkmcnt(12)
	v_add_f32_e32 v71, v71, v105
	s_waitcnt lgkmcnt(11)
	v_add_f32_e32 v72, v72, v106
	s_waitcnt lgkmcnt(10)
	v_add_f32_e32 v73, v73, v107
	s_waitcnt lgkmcnt(9)
	v_add_f32_e32 v74, v74, v108
	s_waitcnt lgkmcnt(8)
	v_add_f32_e32 v75, v75, v109
	s_waitcnt lgkmcnt(7)
	v_add_f32_e32 v94, v94, v110
	s_waitcnt lgkmcnt(6)
	v_add_f32_e32 v95, v95, v111
	s_waitcnt lgkmcnt(5)
	v_add_f32_e32 v96, v96, v112
	s_waitcnt lgkmcnt(4)
	v_add_f32_e32 v97, v97, v113
	s_waitcnt lgkmcnt(3)
	v_add_f32_e32 v98, v98, v114
	s_waitcnt lgkmcnt(2)
	v_add_f32_e32 v99, v99, v115
	s_waitcnt lgkmcnt(1)
	v_add_f32_e32 v100, v100, v116
	s_waitcnt lgkmcnt(0)
	v_add_f32_e32 v101, v101, v117
	ds_bpermute_b32 v102, v88, v68
	ds_bpermute_b32 v103, v88, v69
	ds_bpermute_b32 v104, v88, v70
	ds_bpermute_b32 v105, v88, v71
	ds_bpermute_b32 v106, v88, v72
	ds_bpermute_b32 v107, v88, v73
	ds_bpermute_b32 v108, v88, v74
	ds_bpermute_b32 v109, v88, v75
	ds_bpermute_b32 v110, v88, v94
	ds_bpermute_b32 v111, v88, v95
	ds_bpermute_b32 v112, v88, v96
	ds_bpermute_b32 v113, v88, v97
	ds_bpermute_b32 v114, v88, v98
	ds_bpermute_b32 v115, v88, v99
	ds_bpermute_b32 v116, v88, v100
	ds_bpermute_b32 v117, v88, v101
	s_waitcnt lgkmcnt(15)
	v_add_f32_e32 v68, v68, v102
	s_waitcnt lgkmcnt(14)
	v_add_f32_e32 v69, v69, v103
	s_waitcnt lgkmcnt(13)
	v_add_f32_e32 v70, v70, v104
	s_waitcnt lgkmcnt(12)
	v_add_f32_e32 v71, v71, v105
	s_waitcnt lgkmcnt(11)
	v_add_f32_e32 v72, v72, v106
	s_waitcnt lgkmcnt(10)
	v_add_f32_e32 v73, v73, v107
	s_waitcnt lgkmcnt(9)
	v_add_f32_e32 v74, v74, v108
	s_waitcnt lgkmcnt(8)
	v_add_f32_e32 v75, v75, v109
	s_waitcnt lgkmcnt(7)
	v_add_f32_e32 v94, v94, v110
	s_waitcnt lgkmcnt(6)
	v_add_f32_e32 v95, v95, v111
	s_waitcnt lgkmcnt(5)
	v_add_f32_e32 v96, v96, v112
	s_waitcnt lgkmcnt(4)
	v_add_f32_e32 v97, v97, v113
	s_waitcnt lgkmcnt(3)
	v_add_f32_e32 v98, v98, v114
	s_waitcnt lgkmcnt(2)
	v_add_f32_e32 v99, v99, v115
	s_waitcnt lgkmcnt(1)
	v_add_f32_e32 v100, v100, v116
	s_waitcnt lgkmcnt(0)
	v_add_f32_e32 v101, v101, v117
	ds_bpermute_b32 v102, v89, v68
	ds_bpermute_b32 v103, v89, v69
	ds_bpermute_b32 v104, v89, v70
	ds_bpermute_b32 v105, v89, v71
	ds_bpermute_b32 v106, v89, v72
	ds_bpermute_b32 v107, v89, v73
	ds_bpermute_b32 v108, v89, v74
	ds_bpermute_b32 v109, v89, v75
	ds_bpermute_b32 v110, v89, v94
	ds_bpermute_b32 v111, v89, v95
	ds_bpermute_b32 v112, v89, v96
	ds_bpermute_b32 v113, v89, v97
	ds_bpermute_b32 v114, v89, v98
	ds_bpermute_b32 v115, v89, v99
	ds_bpermute_b32 v116, v89, v100
	ds_bpermute_b32 v117, v89, v101
	s_waitcnt lgkmcnt(15)
	v_add_f32_e32 v68, v68, v102
	s_waitcnt lgkmcnt(14)
	v_add_f32_e32 v69, v69, v103
	s_waitcnt lgkmcnt(13)
	v_add_f32_e32 v70, v70, v104
	s_waitcnt lgkmcnt(12)
	v_add_f32_e32 v71, v71, v105
	s_waitcnt lgkmcnt(11)
	v_add_f32_e32 v72, v72, v106
	s_waitcnt lgkmcnt(10)
	v_add_f32_e32 v73, v73, v107
	s_waitcnt lgkmcnt(9)
	v_add_f32_e32 v74, v74, v108
	s_waitcnt lgkmcnt(8)
	v_add_f32_e32 v75, v75, v109
	s_waitcnt lgkmcnt(7)
	v_add_f32_e32 v94, v94, v110
	s_waitcnt lgkmcnt(6)
	v_add_f32_e32 v95, v95, v111
	s_waitcnt lgkmcnt(5)
	v_add_f32_e32 v96, v96, v112
	s_waitcnt lgkmcnt(4)
	v_add_f32_e32 v97, v97, v113
	s_waitcnt lgkmcnt(3)
	v_add_f32_e32 v98, v98, v114
	s_waitcnt lgkmcnt(2)
	v_add_f32_e32 v99, v99, v115
	s_waitcnt lgkmcnt(1)
	v_add_f32_e32 v100, v100, v116
	s_waitcnt lgkmcnt(0)
	v_add_f32_e32 v101, v101, v117
	ds_bpermute_b32 v102, v90, v68
	ds_bpermute_b32 v103, v90, v69
	ds_bpermute_b32 v104, v90, v70
	ds_bpermute_b32 v105, v90, v71
	ds_bpermute_b32 v106, v90, v72
	ds_bpermute_b32 v107, v90, v73
	ds_bpermute_b32 v108, v90, v74
	ds_bpermute_b32 v109, v90, v75
	ds_bpermute_b32 v110, v90, v94
	ds_bpermute_b32 v111, v90, v95
	ds_bpermute_b32 v112, v90, v96
	ds_bpermute_b32 v113, v90, v97
	ds_bpermute_b32 v114, v90, v98
	ds_bpermute_b32 v115, v90, v99
	ds_bpermute_b32 v116, v90, v100
	ds_bpermute_b32 v117, v90, v101
	s_waitcnt lgkmcnt(15)
	v_add_f32_e32 v68, v68, v102
	s_waitcnt lgkmcnt(14)
	v_add_f32_e32 v69, v69, v103
	s_waitcnt lgkmcnt(13)
	v_add_f32_e32 v70, v70, v104
	s_waitcnt lgkmcnt(12)
	v_add_f32_e32 v71, v71, v105
	s_waitcnt lgkmcnt(11)
	v_add_f32_e32 v72, v72, v106
	s_waitcnt lgkmcnt(10)
	v_add_f32_e32 v73, v73, v107
	s_waitcnt lgkmcnt(9)
	v_add_f32_e32 v74, v74, v108
	s_waitcnt lgkmcnt(8)
	v_add_f32_e32 v75, v75, v109
	s_waitcnt lgkmcnt(7)
	v_add_f32_e32 v94, v94, v110
	s_waitcnt lgkmcnt(6)
	v_add_f32_e32 v95, v95, v111
	s_waitcnt lgkmcnt(5)
	v_add_f32_e32 v96, v96, v112
	s_waitcnt lgkmcnt(4)
	v_add_f32_e32 v97, v97, v113
	s_waitcnt lgkmcnt(3)
	v_add_f32_e32 v98, v98, v114
	s_waitcnt lgkmcnt(2)
	v_add_f32_e32 v99, v99, v115
	s_waitcnt lgkmcnt(1)
	v_add_f32_e32 v100, v100, v116
	s_waitcnt lgkmcnt(0)
	v_add_f32_e32 v101, v101, v117
	s_mov_b64 exec, 1
	ds_write_b128 v91, v[68:71]
	ds_write_b128 v91, v[72:75] offset:16
	ds_write_b128 v91, v[94:97] offset:32
	ds_write_b128 v91, v[98:101] offset:48
	s_mov_b64 exec, -1
	s_waitcnt lgkmcnt(0)
	s_barrier
	ds_read_b32 v102, v92
	ds_read_b32 v103, v92 offset:64
	ds_read_b32 v104, v92 offset:128
	ds_read_b32 v105, v92 offset:192
	ds_read_b32 v106, v92 offset:256
	ds_read_b32 v107, v92 offset:320
	ds_read_b32 v108, v92 offset:384
	ds_read_b32 v109, v92 offset:448
	s_waitcnt lgkmcnt(0)
	v_add_f32_e32 v102, v102, v103
	v_add_f32_e32 v104, v104, v105
	v_add_f32_e32 v106, v106, v107
	v_add_f32_e32 v108, v108, v109
	v_add_f32_e32 v102, v102, v104
	v_add_f32_e32 v106, v106, v108
	v_add_f32_e32 v102, v102, v106
	v_fmamk_f32 v102, v102, 0x3a000000, v173
	v_cmp_gt_f32_e32 vcc, s33, v102
	v_mul_f32_e32 v116, 0x4f800000, v102
	s_nop 1
	v_cndmask_b32_e32 v102, v102, v116, vcc
	v_sqrt_f32_e32 v116, v102
	s_nop 1
	v_add_u32_e32 v111, -1, v116
	v_fma_f32 v112, -v111, v116, v102
	v_cmp_ge_f32_e64 s[14:15], 0, v112
	v_add_u32_e32 v112, 1, v116
	s_nop 1
	v_cndmask_b32_e64 v111, v116, v111, s[14:15]
	v_fma_f32 v116, -v112, v116, v102
	v_cmp_lt_f32_e64 s[14:15], 0, v116
	s_nop 1
	v_cndmask_b32_e64 v116, v111, v112, s[14:15]
	v_mul_f32_e32 v111, 0x37800000, v116
	v_cndmask_b32_e32 v116, v116, v111, vcc
	v_cmp_class_f32_e32 vcc, v102, v174
	s_nop 1
	v_cndmask_b32_e32 v102, v116, v102, vcc
	v_div_scale_f32 v116, s[16:17], v102, v102, 1.0
	v_rcp_f32_e32 v111, v116
	s_nop 0
	v_fma_f32 v112, -v116, v111, 1.0
	v_fmac_f32_e32 v111, v112, v111
	v_div_scale_f32 v112, vcc, 1.0, v102, 1.0
	v_mul_f32_e32 v113, v112, v111
	v_fma_f32 v114, -v116, v113, v112
	v_fmac_f32_e32 v113, v114, v111
	v_fma_f32 v116, -v116, v113, v112
	v_div_fmas_f32 v116, v116, v111, v113
	v_div_fixup_f32 v116, v116, v102, 1.0
	s_waitcnt vmcnt(0)
	v_pk_add_f32 v[118:119], v[118:119], 1.0 op_sel_hi:[1,0]
	v_pk_add_f32 v[120:121], v[120:121], 1.0 op_sel_hi:[1,0]
	v_pk_mul_f32 v[104:105], v[0:1], v[118:119]
	v_pk_mul_f32 v[106:107], v[2:3], v[120:121]
	s_ashr_i32 s11, s10, 31
	s_lshl_b64 s[4:5], s[10:11], 12
	v_readlane_b32 s0, v116, 0
	v_readlane_b32 s1, v116, 1
	v_readlane_b32 s11, v116, 2
	v_readlane_b32 s12, v116, 3
	v_readlane_b32 s13, v116, 4
	v_readlane_b32 s14, v116, 5
	v_readlane_b32 s18, v116, 6
	v_readlane_b32 s19, v116, 7
	s_nop 1
	v_mul_f32_e32 v4, s0, v4
	v_mul_f32_e32 v5, s0, v5
	v_mul_f32_e32 v6, s0, v6
	v_mul_f32_e32 v7, s0, v7
	v_pk_fma_f32 v[4:5], v[104:105], v[4:5], v[250:251]
	v_pk_fma_f32 v[6:7], v[106:107], v[6:7], v[252:253]
	v_cvt_pk_bf16_f32 v4, v4, v5
	v_cvt_pk_bf16_f32 v5, v6, v7
	v_lshl_add_u64 v[108:109], v[76:77], 0, s[4:5]
	global_store_dwordx2 v[108:109], v[4:5], off
	s_add_u32 s4, s4, 0x1000
	s_addc_u32 s5, s5, 0
	v_mul_f32_e32 v8, s1, v8
	v_mul_f32_e32 v9, s1, v9
	v_mul_f32_e32 v10, s1, v10
	v_mul_f32_e32 v11, s1, v11
	v_pk_fma_f32 v[8:9], v[104:105], v[8:9], v[250:251]
	v_pk_fma_f32 v[10:11], v[106:107], v[10:11], v[252:253]
	v_cvt_pk_bf16_f32 v8, v8, v9
	v_cvt_pk_bf16_f32 v9, v10, v11
	v_lshl_add_u64 v[108:109], v[76:77], 0, s[4:5]
	global_store_dwordx2 v[108:109], v[8:9], off
	s_add_u32 s4, s4, 0x1000
	s_addc_u32 s5, s5, 0
	v_mul_f32_e32 v12, s11, v12
	v_mul_f32_e32 v13, s11, v13
	v_mul_f32_e32 v14, s11, v14
	v_mul_f32_e32 v15, s11, v15
	v_pk_fma_f32 v[12:13], v[104:105], v[12:13], v[250:251]
	v_pk_fma_f32 v[14:15], v[106:107], v[14:15], v[252:253]
	v_cvt_pk_bf16_f32 v12, v12, v13
	v_cvt_pk_bf16_f32 v13, v14, v15
	v_lshl_add_u64 v[108:109], v[76:77], 0, s[4:5]
	global_store_dwordx2 v[108:109], v[12:13], off
	s_add_u32 s4, s4, 0x1000
	s_addc_u32 s5, s5, 0
	v_mul_f32_e32 v16, s12, v16
	v_mul_f32_e32 v17, s12, v17
	v_mul_f32_e32 v18, s12, v18
	v_mul_f32_e32 v19, s12, v19
	v_pk_fma_f32 v[16:17], v[104:105], v[16:17], v[250:251]
	v_pk_fma_f32 v[18:19], v[106:107], v[18:19], v[252:253]
	v_cvt_pk_bf16_f32 v16, v16, v17
	v_cvt_pk_bf16_f32 v17, v18, v19
	v_lshl_add_u64 v[108:109], v[76:77], 0, s[4:5]
	global_store_dwordx2 v[108:109], v[16:17], off
	s_add_u32 s4, s4, 0x1000
	s_addc_u32 s5, s5, 0
	v_mul_f32_e32 v20, s13, v20
	v_mul_f32_e32 v21, s13, v21
	v_mul_f32_e32 v22, s13, v22
	v_mul_f32_e32 v23, s13, v23
	v_pk_fma_f32 v[20:21], v[104:105], v[20:21], v[250:251]
	v_pk_fma_f32 v[22:23], v[106:107], v[22:23], v[252:253]
	v_cvt_pk_bf16_f32 v20, v20, v21
	v_cvt_pk_bf16_f32 v21, v22, v23
	v_lshl_add_u64 v[108:109], v[76:77], 0, s[4:5]
	global_store_dwordx2 v[108:109], v[20:21], off
	s_add_u32 s4, s4, 0x1000
	s_addc_u32 s5, s5, 0
	v_mul_f32_e32 v24, s14, v24
	v_mul_f32_e32 v25, s14, v25
	v_mul_f32_e32 v26, s14, v26
	v_mul_f32_e32 v27, s14, v27
	v_pk_fma_f32 v[24:25], v[104:105], v[24:25], v[250:251]
	v_pk_fma_f32 v[26:27], v[106:107], v[26:27], v[252:253]
	v_cvt_pk_bf16_f32 v24, v24, v25
	v_cvt_pk_bf16_f32 v25, v26, v27
	v_lshl_add_u64 v[108:109], v[76:77], 0, s[4:5]
	global_store_dwordx2 v[108:109], v[24:25], off
	s_add_u32 s4, s4, 0x1000
	s_addc_u32 s5, s5, 0
	v_mul_f32_e32 v28, s18, v28
	v_mul_f32_e32 v29, s18, v29
	v_mul_f32_e32 v30, s18, v30
	v_mul_f32_e32 v31, s18, v31
	v_pk_fma_f32 v[28:29], v[104:105], v[28:29], v[250:251]
	v_pk_fma_f32 v[30:31], v[106:107], v[30:31], v[252:253]
	v_cvt_pk_bf16_f32 v28, v28, v29
	v_cvt_pk_bf16_f32 v29, v30, v31
	v_lshl_add_u64 v[108:109], v[76:77], 0, s[4:5]
	global_store_dwordx2 v[108:109], v[28:29], off
	s_add_u32 s4, s4, 0x1000
	s_addc_u32 s5, s5, 0
	v_mul_f32_e32 v32, s19, v32
	v_mul_f32_e32 v33, s19, v33
	v_mul_f32_e32 v34, s19, v34
	v_mul_f32_e32 v35, s19, v35
	v_pk_fma_f32 v[32:33], v[104:105], v[32:33], v[250:251]
	v_pk_fma_f32 v[34:35], v[106:107], v[34:35], v[252:253]
	v_cvt_pk_bf16_f32 v32, v32, v33
	v_cvt_pk_bf16_f32 v33, v34, v35
	v_lshl_add_u64 v[108:109], v[76:77], 0, s[4:5]
	global_store_dwordx2 v[108:109], v[32:33], off
	s_add_u32 s4, s4, 0x1000
	s_addc_u32 s5, s5, 0
	v_readlane_b32 s0, v116, 8
	v_readlane_b32 s1, v116, 9
	v_readlane_b32 s11, v116, 10
	v_readlane_b32 s12, v116, 11
	v_readlane_b32 s13, v116, 12
	v_readlane_b32 s14, v116, 13
	v_readlane_b32 s18, v116, 14
	v_readlane_b32 s19, v116, 15
	s_nop 1
	v_mul_f32_e32 v36, s0, v36
	v_mul_f32_e32 v37, s0, v37
	v_mul_f32_e32 v38, s0, v38
	v_mul_f32_e32 v39, s0, v39
	v_pk_fma_f32 v[36:37], v[104:105], v[36:37], v[250:251]
	v_pk_fma_f32 v[38:39], v[106:107], v[38:39], v[252:253]
	v_cvt_pk_bf16_f32 v36, v36, v37
	v_cvt_pk_bf16_f32 v37, v38, v39
	v_lshl_add_u64 v[108:109], v[76:77], 0, s[4:5]
	global_store_dwordx2 v[108:109], v[36:37], off
	s_add_u32 s4, s4, 0x1000
	s_addc_u32 s5, s5, 0
	v_mul_f32_e32 v40, s1, v40
	v_mul_f32_e32 v41, s1, v41
	v_mul_f32_e32 v42, s1, v42
	v_mul_f32_e32 v43, s1, v43
	v_pk_fma_f32 v[40:41], v[104:105], v[40:41], v[250:251]
	v_pk_fma_f32 v[42:43], v[106:107], v[42:43], v[252:253]
	v_cvt_pk_bf16_f32 v40, v40, v41
	v_cvt_pk_bf16_f32 v41, v42, v43
	v_lshl_add_u64 v[108:109], v[76:77], 0, s[4:5]
	global_store_dwordx2 v[108:109], v[40:41], off
	s_add_u32 s4, s4, 0x1000
	s_addc_u32 s5, s5, 0
	v_mul_f32_e32 v44, s11, v44
	v_mul_f32_e32 v45, s11, v45
	v_mul_f32_e32 v46, s11, v46
	v_mul_f32_e32 v47, s11, v47
	v_pk_fma_f32 v[44:45], v[104:105], v[44:45], v[250:251]
	v_pk_fma_f32 v[46:47], v[106:107], v[46:47], v[252:253]
	v_cvt_pk_bf16_f32 v44, v44, v45
	v_cvt_pk_bf16_f32 v45, v46, v47
	v_lshl_add_u64 v[108:109], v[76:77], 0, s[4:5]
	global_store_dwordx2 v[108:109], v[44:45], off
	s_add_u32 s4, s4, 0x1000
	s_addc_u32 s5, s5, 0
	v_mul_f32_e32 v48, s12, v48
	v_mul_f32_e32 v49, s12, v49
	v_mul_f32_e32 v50, s12, v50
	v_mul_f32_e32 v51, s12, v51
	v_pk_fma_f32 v[48:49], v[104:105], v[48:49], v[250:251]
	v_pk_fma_f32 v[50:51], v[106:107], v[50:51], v[252:253]
	v_cvt_pk_bf16_f32 v48, v48, v49
	v_cvt_pk_bf16_f32 v49, v50, v51
	v_lshl_add_u64 v[108:109], v[76:77], 0, s[4:5]
	global_store_dwordx2 v[108:109], v[48:49], off
	s_add_u32 s4, s4, 0x1000
	s_addc_u32 s5, s5, 0
	v_mul_f32_e32 v52, s13, v52
	v_mul_f32_e32 v53, s13, v53
	v_mul_f32_e32 v54, s13, v54
	v_mul_f32_e32 v55, s13, v55
	v_pk_fma_f32 v[52:53], v[104:105], v[52:53], v[250:251]
	v_pk_fma_f32 v[54:55], v[106:107], v[54:55], v[252:253]
	v_cvt_pk_bf16_f32 v52, v52, v53
	v_cvt_pk_bf16_f32 v53, v54, v55
	v_lshl_add_u64 v[108:109], v[76:77], 0, s[4:5]
	global_store_dwordx2 v[108:109], v[52:53], off
	s_add_u32 s4, s4, 0x1000
	s_addc_u32 s5, s5, 0
	v_mul_f32_e32 v56, s14, v56
	v_mul_f32_e32 v57, s14, v57
	v_mul_f32_e32 v58, s14, v58
	v_mul_f32_e32 v59, s14, v59
	v_pk_fma_f32 v[56:57], v[104:105], v[56:57], v[250:251]
	v_pk_fma_f32 v[58:59], v[106:107], v[58:59], v[252:253]
	v_cvt_pk_bf16_f32 v56, v56, v57
	v_cvt_pk_bf16_f32 v57, v58, v59
	v_lshl_add_u64 v[108:109], v[76:77], 0, s[4:5]
	global_store_dwordx2 v[108:109], v[56:57], off
	s_add_u32 s4, s4, 0x1000
	s_addc_u32 s5, s5, 0
	v_mul_f32_e32 v60, s18, v60
	v_mul_f32_e32 v61, s18, v61
	v_mul_f32_e32 v62, s18, v62
	v_mul_f32_e32 v63, s18, v63
	v_pk_fma_f32 v[60:61], v[104:105], v[60:61], v[250:251]
	v_pk_fma_f32 v[62:63], v[106:107], v[62:63], v[252:253]
	v_cvt_pk_bf16_f32 v60, v60, v61
	v_cvt_pk_bf16_f32 v61, v62, v63
	v_lshl_add_u64 v[108:109], v[76:77], 0, s[4:5]
	global_store_dwordx2 v[108:109], v[60:61], off
	s_add_u32 s4, s4, 0x1000
	s_addc_u32 s5, s5, 0
	v_mul_f32_e32 v64, s19, v64
	v_mul_f32_e32 v65, s19, v65
	v_mul_f32_e32 v66, s19, v66
	v_mul_f32_e32 v67, s19, v67
	v_pk_fma_f32 v[64:65], v[104:105], v[64:65], v[250:251]
	v_pk_fma_f32 v[66:67], v[106:107], v[66:67], v[252:253]
	v_cvt_pk_bf16_f32 v64, v64, v65
	v_cvt_pk_bf16_f32 v65, v66, v67
	v_lshl_add_u64 v[108:109], v[76:77], 0, s[4:5]
	global_store_dwordx2 v[108:109], v[64:65], off
	s_add_u32 s4, s4, 0x1000
	s_addc_u32 s5, s5, 0
	s_mov_b32 s12, 0x2000
	s_mov_b32 s13, 0
	s_waitcnt lgkmcnt(0)
	s_barrier
	s_add_i32 s22, s22, s34
	s_add_i32 s10, s10, s88
	s_cmpk_gt_i32 s22, 0x3ff
	s_cbranch_scc0 .Lnm_n1_loop
	s_branch .LBB0_182

.LBB0_908:
	s_lshl_b64 s[0:1], s[20:21], 2
	s_add_u32 s0, s62, s0
	v_lshlrev_b64 v[168:169], 2, v[96:97]
	s_addc_u32 s1, s63, s1
	v_lshl_add_u64 v[170:171], s[18:19], 0, v[168:169]
	v_lshl_add_u64 v[96:97], s[0:1], 0, v[168:169]
	v_lshl_add_u64 v[196:197], v[170:171], 0, v[146:147]
	global_load_dwordx4 v[108:111], v[96:97], off nt
	global_load_dwordx4 v[104:107], v[96:97], off offset:64 nt
	global_load_dwordx4 v[100:103], v[96:97], off offset:512 nt
	s_nop 0
	global_load_dwordx4 v[96:99], v[96:97], off offset:576 nt
	s_nop 0
	global_load_dwordx4 v[184:187], v[196:197], off nt
	global_load_dwordx4 v[188:191], v[196:197], off offset:64 nt
	global_load_dwordx4 v[192:195], v[196:197], off offset:512 nt
	s_nop 0
	global_load_dwordx4 v[196:199], v[196:197], off offset:576 nt
	v_lshl_add_u64 v[212:213], v[170:171], 0, v[148:149]
	global_load_dwordx4 v[200:203], v[212:213], off nt
	global_load_dwordx4 v[204:207], v[212:213], off offset:64 nt
	global_load_dwordx4 v[208:211], v[212:213], off offset:512 nt
	s_nop 0
	global_load_dwordx4 v[212:215], v[212:213], off offset:576 nt
	v_readlane_b32 s0, v248, 53
	v_readlane_b32 s1, v248, 54
	s_add_u32 s0, s0, s44
	s_addc_u32 s1, s1, s45
	v_lshl_add_u64 v[168:169], s[0:1], 0, v[168:169]
	v_lshl_add_u64 v[216:217], v[168:169], 0, v[146:147]
	s_waitcnt vmcnt(0)
	v_pk_fma_f32 v[142:143], v[142:143], v[110:111], v[186:187]
	v_pk_fma_f32 v[140:141], v[140:141], v[108:109], v[184:185]
	v_pk_fma_f32 v[126:127], v[126:127], v[102:103], v[194:195]
	v_pk_fma_f32 v[124:125], v[124:125], v[100:101], v[192:193]
	v_pk_fma_f32 v[122:123], v[122:123], v[98:99], v[198:199]
	v_pk_fma_f32 v[120:121], v[120:121], v[96:97], v[196:197]
	global_store_dwordx4 v[216:217], v[124:127], off offset:512
	global_store_dwordx4 v[216:217], v[120:123], off offset:576
	v_pk_fma_f32 v[138:139], v[138:139], v[106:107], v[190:191]
	v_lshl_add_u64 v[124:125], v[168:169], 0, v[148:149]
	v_pk_fma_f32 v[122:123], v[134:135], v[110:111], v[202:203]
	v_pk_fma_f32 v[120:121], v[132:133], v[108:109], v[200:201]
	v_pk_fma_f32 v[136:137], v[136:137], v[104:105], v[188:189]
	global_store_dwordx4 v[124:125], v[120:123], off
	v_pk_fma_f32 v[118:119], v[118:119], v[102:103], v[210:211]
	v_pk_fma_f32 v[116:117], v[116:117], v[100:101], v[208:209]
	v_pk_fma_f32 v[122:123], v[130:131], v[106:107], v[206:207]
	v_pk_fma_f32 v[120:121], v[128:129], v[104:105], v[204:205]
	v_pk_fma_f32 v[114:115], v[114:115], v[98:99], v[214:215]
	v_pk_fma_f32 v[112:113], v[112:113], v[96:97], v[212:213]
	global_store_dwordx4 v[216:217], v[140:143], off
	global_store_dwordx4 v[216:217], v[136:139], off offset:64
	global_store_dwordx4 v[124:125], v[120:123], off offset:64
	global_store_dwordx4 v[124:125], v[116:119], off offset:512
	global_store_dwordx4 v[124:125], v[112:115], off offset:576
	v_lshl_add_u64 v[124:125], v[170:171], 0, v[150:151]
	global_load_dwordx4 v[112:115], v[124:125], off nt
	global_load_dwordx4 v[116:119], v[124:125], off offset:64 nt
	global_load_dwordx4 v[120:123], v[124:125], off offset:512 nt
	s_nop 0
	global_load_dwordx4 v[124:127], v[124:125], off offset:576 nt
	v_lshl_add_u64 v[140:141], v[170:171], 0, v[152:153]
	global_load_dwordx4 v[128:131], v[140:141], off nt
	global_load_dwordx4 v[132:135], v[140:141], off offset:64 nt
	global_load_dwordx4 v[136:139], v[140:141], off offset:512 nt
	s_nop 0
	global_load_dwordx4 v[140:143], v[140:141], off offset:576 nt
	v_lshl_add_u64 v[184:185], v[168:169], 0, v[150:151]
	s_waitcnt vmcnt(7)
	v_pk_fma_f32 v[94:95], v[94:95], v[110:111], v[114:115]
	v_pk_fma_f32 v[92:93], v[92:93], v[108:109], v[112:113]
	s_waitcnt vmcnt(5)
	v_pk_fma_f32 v[78:79], v[78:79], v[102:103], v[122:123]
	v_pk_fma_f32 v[76:77], v[76:77], v[100:101], v[120:121]
	s_waitcnt vmcnt(4)
	v_pk_fma_f32 v[74:75], v[74:75], v[98:99], v[126:127]
	v_pk_fma_f32 v[72:73], v[72:73], v[96:97], v[124:125]
	global_store_dwordx4 v[184:185], v[76:79], off offset:512
	global_store_dwordx4 v[184:185], v[72:75], off offset:576
	v_pk_fma_f32 v[90:91], v[90:91], v[106:107], v[118:119]
	v_lshl_add_u64 v[76:77], v[168:169], 0, v[152:153]
	s_waitcnt vmcnt(5)
	v_pk_fma_f32 v[74:75], v[86:87], v[110:111], v[130:131]
	v_pk_fma_f32 v[72:73], v[84:85], v[108:109], v[128:129]
	v_pk_fma_f32 v[88:89], v[88:89], v[104:105], v[116:117]
	global_store_dwordx4 v[76:77], v[72:75], off
	s_waitcnt vmcnt(4)
	v_pk_fma_f32 v[70:71], v[70:71], v[102:103], v[138:139]
	v_pk_fma_f32 v[68:69], v[68:69], v[100:101], v[136:137]
	v_pk_fma_f32 v[74:75], v[82:83], v[106:107], v[134:135]
	v_pk_fma_f32 v[72:73], v[80:81], v[104:105], v[132:133]
	s_waitcnt vmcnt(3)
	v_pk_fma_f32 v[66:67], v[66:67], v[98:99], v[142:143]
	v_pk_fma_f32 v[64:65], v[64:65], v[96:97], v[140:141]
	global_store_dwordx4 v[184:185], v[92:95], off
	global_store_dwordx4 v[184:185], v[88:91], off offset:64
	global_store_dwordx4 v[76:77], v[72:75], off offset:64
	global_store_dwordx4 v[76:77], v[68:71], off offset:512
	global_store_dwordx4 v[76:77], v[64:67], off offset:576
	v_lshl_add_u64 v[76:77], v[170:171], 0, v[154:155]
	global_load_dwordx4 v[64:67], v[76:77], off nt
	global_load_dwordx4 v[68:71], v[76:77], off offset:64 nt
	global_load_dwordx4 v[72:75], v[76:77], off offset:512 nt
	s_nop 0
	global_load_dwordx4 v[76:79], v[76:77], off offset:576 nt
	v_lshl_add_u64 v[92:93], v[170:171], 0, v[156:157]
	global_load_dwordx4 v[80:83], v[92:93], off nt
	global_load_dwordx4 v[84:87], v[92:93], off offset:64 nt
	global_load_dwordx4 v[88:91], v[92:93], off offset:512 nt
	s_nop 0
	global_load_dwordx4 v[92:95], v[92:93], off offset:576 nt
	v_lshl_add_u64 v[112:113], v[168:169], 0, v[154:155]
	s_waitcnt vmcnt(7)
	v_pk_fma_f32 v[62:63], v[62:63], v[110:111], v[66:67]
	v_pk_fma_f32 v[60:61], v[60:61], v[108:109], v[64:65]
	s_waitcnt vmcnt(5)
	v_pk_fma_f32 v[46:47], v[46:47], v[102:103], v[74:75]
	v_pk_fma_f32 v[44:45], v[44:45], v[100:101], v[72:73]
	s_waitcnt vmcnt(4)
	v_pk_fma_f32 v[42:43], v[42:43], v[98:99], v[78:79]
	v_pk_fma_f32 v[40:41], v[40:41], v[96:97], v[76:77]
	global_store_dwordx4 v[112:113], v[44:47], off offset:512
	global_store_dwordx4 v[112:113], v[40:43], off offset:576
	v_pk_fma_f32 v[58:59], v[58:59], v[106:107], v[70:71]
	v_lshl_add_u64 v[44:45], v[168:169], 0, v[156:157]
	s_waitcnt vmcnt(5)
	v_pk_fma_f32 v[42:43], v[54:55], v[110:111], v[82:83]
	v_pk_fma_f32 v[40:41], v[52:53], v[108:109], v[80:81]
	v_pk_fma_f32 v[56:57], v[56:57], v[104:105], v[68:69]
	global_store_dwordx4 v[44:45], v[40:43], off
	s_waitcnt vmcnt(4)
	v_pk_fma_f32 v[38:39], v[38:39], v[102:103], v[90:91]
	v_pk_fma_f32 v[36:37], v[36:37], v[100:101], v[88:89]
	v_pk_fma_f32 v[42:43], v[50:51], v[106:107], v[86:87]
	v_pk_fma_f32 v[40:41], v[48:49], v[104:105], v[84:85]
	s_waitcnt vmcnt(3)
	v_pk_fma_f32 v[34:35], v[34:35], v[98:99], v[94:95]
	v_pk_fma_f32 v[32:33], v[32:33], v[96:97], v[92:93]
	global_store_dwordx4 v[112:113], v[60:63], off
	global_store_dwordx4 v[112:113], v[56:59], off offset:64
	global_store_dwordx4 v[44:45], v[40:43], off offset:64
	global_store_dwordx4 v[44:45], v[36:39], off offset:512
	global_store_dwordx4 v[44:45], v[32:35], off offset:576
	v_lshl_add_u64 v[44:45], v[170:171], 0, v[158:159]
	global_load_dwordx4 v[32:35], v[44:45], off nt
	global_load_dwordx4 v[36:39], v[44:45], off offset:64 nt
	global_load_dwordx4 v[40:43], v[44:45], off offset:512 nt
	s_nop 0
	global_load_dwordx4 v[44:47], v[44:45], off offset:576 nt
	v_lshl_add_u64 v[60:61], v[170:171], 0, v[162:163]
	global_load_dwordx4 v[48:51], v[60:61], off nt
	global_load_dwordx4 v[52:55], v[60:61], off offset:64 nt
	global_load_dwordx4 v[56:59], v[60:61], off offset:512 nt
	s_nop 0
	global_load_dwordx4 v[60:63], v[60:61], off offset:576 nt
	v_lshl_add_u64 v[64:65], v[168:169], 0, v[158:159]
	s_waitcnt vmcnt(7)
	v_pk_fma_f32 v[30:31], v[30:31], v[110:111], v[34:35]
	v_pk_fma_f32 v[28:29], v[28:29], v[108:109], v[32:33]
	s_waitcnt vmcnt(6)
	v_pk_fma_f32 v[26:27], v[26:27], v[106:107], v[38:39]
	s_waitcnt vmcnt(4)
	v_pk_fma_f32 v[18:19], v[18:19], v[98:99], v[46:47]
	v_pk_fma_f32 v[16:17], v[16:17], v[96:97], v[44:45]
	v_pk_fma_f32 v[24:25], v[24:25], v[104:105], v[36:37]
	v_pk_fma_f32 v[22:23], v[22:23], v[102:103], v[42:43]
	v_pk_fma_f32 v[20:21], v[20:21], v[100:101], v[40:41]
	global_store_dwordx4 v[64:65], v[16:19], off offset:576
	s_waitcnt vmcnt(4)
	v_pk_fma_f32 v[14:15], v[14:15], v[110:111], v[50:51]
	v_pk_fma_f32 v[12:13], v[12:13], v[108:109], v[48:49]
	v_lshl_add_u64 v[16:17], v[168:169], 0, v[162:163]
	s_waitcnt vmcnt(3)
	v_pk_fma_f32 v[10:11], v[10:11], v[106:107], v[54:55]
	v_pk_fma_f32 v[8:9], v[8:9], v[104:105], v[52:53]
	s_waitcnt vmcnt(2)
	v_pk_fma_f32 v[6:7], v[6:7], v[102:103], v[58:59]
	v_pk_fma_f32 v[4:5], v[4:5], v[100:101], v[56:57]
	s_waitcnt vmcnt(1)
	v_pk_fma_f32 v[2:3], v[2:3], v[98:99], v[62:63]
	v_pk_fma_f32 v[0:1], v[0:1], v[96:97], v[60:61]
	global_store_dwordx4 v[64:65], v[28:31], off
	global_store_dwordx4 v[64:65], v[24:27], off offset:64
	global_store_dwordx4 v[64:65], v[20:23], off offset:512
	global_store_dwordx4 v[16:17], v[12:15], off
	global_store_dwordx4 v[16:17], v[8:11], off offset:64
	global_store_dwordx4 v[16:17], v[4:7], off offset:512
	global_store_dwordx4 v[16:17], v[0:3], off offset:576

.Lnm_n2_loop:
	s_ashr_i32 s9, s8, 31
	s_lshl_b64 s[0:1], s[8:9], 13
	v_lshl_add_u64 v[110:111], v[76:77], 0, s[0:1]
	global_load_dwordx4 v[4:7], v[110:111], off nt
	s_add_u32 s0, s0, 0x2000
	s_addc_u32 s1, s1, 0
	v_lshl_add_u64 v[110:111], v[76:77], 0, s[0:1]
	global_load_dwordx4 v[8:11], v[110:111], off nt
	s_add_u32 s0, s0, 0x2000
	s_addc_u32 s1, s1, 0
	v_lshl_add_u64 v[110:111], v[76:77], 0, s[0:1]
	global_load_dwordx4 v[12:15], v[110:111], off nt
	s_add_u32 s0, s0, 0x2000
	s_addc_u32 s1, s1, 0
	v_lshl_add_u64 v[110:111], v[76:77], 0, s[0:1]
	global_load_dwordx4 v[16:19], v[110:111], off nt
	s_add_u32 s0, s0, 0x2000
	s_addc_u32 s1, s1, 0
	v_lshl_add_u64 v[110:111], v[76:77], 0, s[0:1]
	global_load_dwordx4 v[20:23], v[110:111], off nt
	s_add_u32 s0, s0, 0x2000
	s_addc_u32 s1, s1, 0
	v_lshl_add_u64 v[110:111], v[76:77], 0, s[0:1]
	global_load_dwordx4 v[24:27], v[110:111], off nt
	s_add_u32 s0, s0, 0x2000
	s_addc_u32 s1, s1, 0
	v_lshl_add_u64 v[110:111], v[76:77], 0, s[0:1]
	global_load_dwordx4 v[28:31], v[110:111], off nt
	s_add_u32 s0, s0, 0x2000
	s_addc_u32 s1, s1, 0
	v_lshl_add_u64 v[110:111], v[76:77], 0, s[0:1]
	global_load_dwordx4 v[32:35], v[110:111], off nt
	s_add_u32 s0, s0, 0x2000
	s_addc_u32 s1, s1, 0
	v_lshl_add_u64 v[110:111], v[76:77], 0, s[0:1]
	global_load_dwordx4 v[36:39], v[110:111], off nt
	s_add_u32 s0, s0, 0x2000
	s_addc_u32 s1, s1, 0
	v_lshl_add_u64 v[110:111], v[76:77], 0, s[0:1]
	global_load_dwordx4 v[40:43], v[110:111], off nt
	s_add_u32 s0, s0, 0x2000
	s_addc_u32 s1, s1, 0
	v_lshl_add_u64 v[110:111], v[76:77], 0, s[0:1]
	global_load_dwordx4 v[44:47], v[110:111], off nt
	s_add_u32 s0, s0, 0x2000
	s_addc_u32 s1, s1, 0
	v_lshl_add_u64 v[110:111], v[76:77], 0, s[0:1]
	global_load_dwordx4 v[48:51], v[110:111], off nt
	s_add_u32 s0, s0, 0x2000
	s_addc_u32 s1, s1, 0
	v_lshl_add_u64 v[110:111], v[76:77], 0, s[0:1]
	global_load_dwordx4 v[52:55], v[110:111], off nt
	s_add_u32 s0, s0, 0x2000
	s_addc_u32 s1, s1, 0
	v_lshl_add_u64 v[110:111], v[76:77], 0, s[0:1]
	global_load_dwordx4 v[56:59], v[110:111], off nt
	s_add_u32 s0, s0, 0x2000
	s_addc_u32 s1, s1, 0
	v_lshl_add_u64 v[110:111], v[76:77], 0, s[0:1]
	global_load_dwordx4 v[60:63], v[110:111], off nt
	s_add_u32 s0, s0, 0x2000
	s_addc_u32 s1, s1, 0
	v_lshl_add_u64 v[110:111], v[76:77], 0, s[0:1]
	global_load_dwordx4 v[64:67], v[110:111], off nt
	s_ashr_i32 s0, s20, 8
	v_mad_i64_i32 v[110:111], s[0:1], s0, v178, v[82:83]
	v_lshl_add_u64 v[112:113], v[110:111], 0, s[12:13]
	global_load_dwordx4 v[118:121], v[112:113], off
	s_mov_b32 s0, 0x6000
	s_mov_b32 s1, 0
	v_lshl_add_u64 v[112:113], v[110:111], 0, s[0:1]
	global_load_dwordx4 v[250:253], v[112:113], off
	s_waitcnt vmcnt(17)
	v_mul_f32_e32 v68, v5, v5
	v_mul_f32_e32 v102, v7, v7
	v_fmac_f32_e32 v68, v4, v4
	v_fmac_f32_e32 v102, v6, v6
	v_add_f32_e32 v68, v68, v102
	s_waitcnt vmcnt(16)
	v_mul_f32_e32 v69, v9, v9
	v_mul_f32_e32 v103, v11, v11
	v_fmac_f32_e32 v69, v8, v8
	v_fmac_f32_e32 v103, v10, v10
	v_add_f32_e32 v69, v69, v103
	s_waitcnt vmcnt(15)
	v_mul_f32_e32 v70, v13, v13
	v_mul_f32_e32 v104, v15, v15
	v_fmac_f32_e32 v70, v12, v12
	v_fmac_f32_e32 v104, v14, v14
	v_add_f32_e32 v70, v70, v104
	s_waitcnt vmcnt(14)
	v_mul_f32_e32 v71, v17, v17
	v_mul_f32_e32 v105, v19, v19
	v_fmac_f32_e32 v71, v16, v16
	v_fmac_f32_e32 v105, v18, v18
	v_add_f32_e32 v71, v71, v105
	s_waitcnt vmcnt(13)
	v_mul_f32_e32 v72, v21, v21
	v_mul_f32_e32 v106, v23, v23
	v_fmac_f32_e32 v72, v20, v20
	v_fmac_f32_e32 v106, v22, v22
	v_add_f32_e32 v72, v72, v106
	s_waitcnt vmcnt(12)
	v_mul_f32_e32 v73, v25, v25
	v_mul_f32_e32 v107, v27, v27
	v_fmac_f32_e32 v73, v24, v24
	v_fmac_f32_e32 v107, v26, v26
	v_add_f32_e32 v73, v73, v107
	s_waitcnt vmcnt(11)
	v_mul_f32_e32 v74, v29, v29
	v_mul_f32_e32 v108, v31, v31
	v_fmac_f32_e32 v74, v28, v28
	v_fmac_f32_e32 v108, v30, v30
	v_add_f32_e32 v74, v74, v108
	s_waitcnt vmcnt(10)
	v_mul_f32_e32 v75, v33, v33
	v_mul_f32_e32 v109, v35, v35
	v_fmac_f32_e32 v75, v32, v32
	v_fmac_f32_e32 v109, v34, v34
	v_add_f32_e32 v75, v75, v109
	s_waitcnt vmcnt(9)
	v_mul_f32_e32 v94, v37, v37
	v_mul_f32_e32 v110, v39, v39
	v_fmac_f32_e32 v94, v36, v36
	v_fmac_f32_e32 v110, v38, v38
	v_add_f32_e32 v94, v94, v110
	s_waitcnt vmcnt(8)
	v_mul_f32_e32 v95, v41, v41
	v_mul_f32_e32 v111, v43, v43
	v_fmac_f32_e32 v95, v40, v40
	v_fmac_f32_e32 v111, v42, v42
	v_add_f32_e32 v95, v95, v111
	s_waitcnt vmcnt(7)
	v_mul_f32_e32 v96, v45, v45
	v_mul_f32_e32 v112, v47, v47
	v_fmac_f32_e32 v96, v44, v44
	v_fmac_f32_e32 v112, v46, v46
	v_add_f32_e32 v96, v96, v112
	s_waitcnt vmcnt(6)
	v_mul_f32_e32 v97, v49, v49
	v_mul_f32_e32 v113, v51, v51
	v_fmac_f32_e32 v97, v48, v48
	v_fmac_f32_e32 v113, v50, v50
	v_add_f32_e32 v97, v97, v113
	s_waitcnt vmcnt(5)
	v_mul_f32_e32 v98, v53, v53
	v_mul_f32_e32 v114, v55, v55
	v_fmac_f32_e32 v98, v52, v52
	v_fmac_f32_e32 v114, v54, v54
	v_add_f32_e32 v98, v98, v114
	s_waitcnt vmcnt(4)
	v_mul_f32_e32 v99, v57, v57
	v_mul_f32_e32 v115, v59, v59
	v_fmac_f32_e32 v99, v56, v56
	v_fmac_f32_e32 v115, v58, v58
	v_add_f32_e32 v99, v99, v115
	s_waitcnt vmcnt(3)
	v_mul_f32_e32 v100, v61, v61
	v_mul_f32_e32 v116, v63, v63
	v_fmac_f32_e32 v100, v60, v60
	v_fmac_f32_e32 v116, v62, v62
	v_add_f32_e32 v100, v100, v116
	s_waitcnt vmcnt(2)
	v_mul_f32_e32 v101, v65, v65
	v_mul_f32_e32 v117, v67, v67
	v_fmac_f32_e32 v101, v64, v64
	v_fmac_f32_e32 v117, v66, v66
	v_add_f32_e32 v101, v101, v117
	ds_bpermute_b32 v102, v87, v68
	ds_bpermute_b32 v103, v87, v69
	ds_bpermute_b32 v104, v87, v70
	ds_bpermute_b32 v105, v87, v71
	ds_bpermute_b32 v106, v87, v72
	ds_bpermute_b32 v107, v87, v73
	ds_bpermute_b32 v108, v87, v74
	ds_bpermute_b32 v109, v87, v75
	ds_bpermute_b32 v110, v87, v94
	ds_bpermute_b32 v111, v87, v95
	ds_bpermute_b32 v112, v87, v96
	ds_bpermute_b32 v113, v87, v97
	ds_bpermute_b32 v114, v87, v98
	ds_bpermute_b32 v115, v87, v99
	ds_bpermute_b32 v116, v87, v100
	ds_bpermute_b32 v117, v87, v101
	s_waitcnt lgkmcnt(15)
	v_add_f32_e32 v68, v68, v102
	s_waitcnt lgkmcnt(14)
	v_add_f32_e32 v69, v69, v103
	s_waitcnt lgkmcnt(13)
	v_add_f32_e32 v70, v70, v104
	s_waitcnt lgkmcnt(12)
	v_add_f32_e32 v71, v71, v105
	s_waitcnt lgkmcnt(11)
	v_add_f32_e32 v72, v72, v106
	s_waitcnt lgkmcnt(10)
	v_add_f32_e32 v73, v73, v107
	s_waitcnt lgkmcnt(9)
	v_add_f32_e32 v74, v74, v108
	s_waitcnt lgkmcnt(8)
	v_add_f32_e32 v75, v75, v109
	s_waitcnt lgkmcnt(7)
	v_add_f32_e32 v94, v94, v110
	s_waitcnt lgkmcnt(6)
	v_add_f32_e32 v95, v95, v111
	s_waitcnt lgkmcnt(5)
	v_add_f32_e32 v96, v96, v112
	s_waitcnt lgkmcnt(4)
	v_add_f32_e32 v97, v97, v113
	s_waitcnt lgkmcnt(3)
	v_add_f32_e32 v98, v98, v114
	s_waitcnt lgkmcnt(2)
	v_add_f32_e32 v99, v99, v115
	s_waitcnt lgkmcnt(1)
	v_add_f32_e32 v100, v100, v116
	s_waitcnt lgkmcnt(0)
	v_add_f32_e32 v101, v101, v117
	ds_bpermute_b32 v102, v88, v68
	ds_bpermute_b32 v103, v88, v69
	ds_bpermute_b32 v104, v88, v70
	ds_bpermute_b32 v105, v88, v71
	ds_bpermute_b32 v106, v88, v72
	ds_bpermute_b32 v107, v88, v73
	ds_bpermute_b32 v108, v88, v74
	ds_bpermute_b32 v109, v88, v75
	ds_bpermute_b32 v110, v88, v94
	ds_bpermute_b32 v111, v88, v95
	ds_bpermute_b32 v112, v88, v96
	ds_bpermute_b32 v113, v88, v97
	ds_bpermute_b32 v114, v88, v98
	ds_bpermute_b32 v115, v88, v99
	ds_bpermute_b32 v116, v88, v100
	ds_bpermute_b32 v117, v88, v101
	s_waitcnt lgkmcnt(15)
	v_add_f32_e32 v68, v68, v102
	s_waitcnt lgkmcnt(14)
	v_add_f32_e32 v69, v69, v103
	s_waitcnt lgkmcnt(13)
	v_add_f32_e32 v70, v70, v104
	s_waitcnt lgkmcnt(12)
	v_add_f32_e32 v71, v71, v105
	s_waitcnt lgkmcnt(11)
	v_add_f32_e32 v72, v72, v106
	s_waitcnt lgkmcnt(10)
	v_add_f32_e32 v73, v73, v107
	s_waitcnt lgkmcnt(9)
	v_add_f32_e32 v74, v74, v108
	s_waitcnt lgkmcnt(8)
	v_add_f32_e32 v75, v75, v109
	s_waitcnt lgkmcnt(7)
	v_add_f32_e32 v94, v94, v110
	s_waitcnt lgkmcnt(6)
	v_add_f32_e32 v95, v95, v111
	s_waitcnt lgkmcnt(5)
	v_add_f32_e32 v96, v96, v112
	s_waitcnt lgkmcnt(4)
	v_add_f32_e32 v97, v97, v113
	s_waitcnt lgkmcnt(3)
	v_add_f32_e32 v98, v98, v114
	s_waitcnt lgkmcnt(2)
	v_add_f32_e32 v99, v99, v115
	s_waitcnt lgkmcnt(1)
	v_add_f32_e32 v100, v100, v116
	s_waitcnt lgkmcnt(0)
	v_add_f32_e32 v101, v101, v117
	ds_bpermute_b32 v102, v89, v68
	ds_bpermute_b32 v103, v89, v69
	ds_bpermute_b32 v104, v89, v70
	ds_bpermute_b32 v105, v89, v71
	ds_bpermute_b32 v106, v89, v72
	ds_bpermute_b32 v107, v89, v73
	ds_bpermute_b32 v108, v89, v74
	ds_bpermute_b32 v109, v89, v75
	ds_bpermute_b32 v110, v89, v94
	ds_bpermute_b32 v111, v89, v95
	ds_bpermute_b32 v112, v89, v96
	ds_bpermute_b32 v113, v89, v97
	ds_bpermute_b32 v114, v89, v98
	ds_bpermute_b32 v115, v89, v99
	ds_bpermute_b32 v116, v89, v100
	ds_bpermute_b32 v117, v89, v101
	s_waitcnt lgkmcnt(15)
	v_add_f32_e32 v68, v68, v102
	s_waitcnt lgkmcnt(14)
	v_add_f32_e32 v69, v69, v103
	s_waitcnt lgkmcnt(13)
	v_add_f32_e32 v70, v70, v104
	s_waitcnt lgkmcnt(12)
	v_add_f32_e32 v71, v71, v105
	s_waitcnt lgkmcnt(11)
	v_add_f32_e32 v72, v72, v106
	s_waitcnt lgkmcnt(10)
	v_add_f32_e32 v73, v73, v107
	s_waitcnt lgkmcnt(9)
	v_add_f32_e32 v74, v74, v108
	s_waitcnt lgkmcnt(8)
	v_add_f32_e32 v75, v75, v109
	s_waitcnt lgkmcnt(7)
	v_add_f32_e32 v94, v94, v110
	s_waitcnt lgkmcnt(6)
	v_add_f32_e32 v95, v95, v111
	s_waitcnt lgkmcnt(5)
	v_add_f32_e32 v96, v96, v112
	s_waitcnt lgkmcnt(4)
	v_add_f32_e32 v97, v97, v113
	s_waitcnt lgkmcnt(3)
	v_add_f32_e32 v98, v98, v114
	s_waitcnt lgkmcnt(2)
	v_add_f32_e32 v99, v99, v115
	s_waitcnt lgkmcnt(1)
	v_add_f32_e32 v100, v100, v116
	s_waitcnt lgkmcnt(0)
	v_add_f32_e32 v101, v101, v117
	ds_bpermute_b32 v102, v90, v68
	ds_bpermute_b32 v103, v90, v69
	ds_bpermute_b32 v104, v90, v70
	ds_bpermute_b32 v105, v90, v71
	ds_bpermute_b32 v106, v90, v72
	ds_bpermute_b32 v107, v90, v73
	ds_bpermute_b32 v108, v90, v74
	ds_bpermute_b32 v109, v90, v75
	ds_bpermute_b32 v110, v90, v94
	ds_bpermute_b32 v111, v90, v95
	ds_bpermute_b32 v112, v90, v96
	ds_bpermute_b32 v113, v90, v97
	ds_bpermute_b32 v114, v90, v98
	ds_bpermute_b32 v115, v90, v99
	ds_bpermute_b32 v116, v90, v100
	ds_bpermute_b32 v117, v90, v101
	s_waitcnt lgkmcnt(15)
	v_add_f32_e32 v68, v68, v102
	s_waitcnt lgkmcnt(14)
	v_add_f32_e32 v69, v69, v103
	s_waitcnt lgkmcnt(13)
	v_add_f32_e32 v70, v70, v104
	s_waitcnt lgkmcnt(12)
	v_add_f32_e32 v71, v71, v105
	s_waitcnt lgkmcnt(11)
	v_add_f32_e32 v72, v72, v106
	s_waitcnt lgkmcnt(10)
	v_add_f32_e32 v73, v73, v107
	s_waitcnt lgkmcnt(9)
	v_add_f32_e32 v74, v74, v108
	s_waitcnt lgkmcnt(8)
	v_add_f32_e32 v75, v75, v109
	s_waitcnt lgkmcnt(7)
	v_add_f32_e32 v94, v94, v110
	s_waitcnt lgkmcnt(6)
	v_add_f32_e32 v95, v95, v111
	s_waitcnt lgkmcnt(5)
	v_add_f32_e32 v96, v96, v112
	s_waitcnt lgkmcnt(4)
	v_add_f32_e32 v97, v97, v113
	s_waitcnt lgkmcnt(3)
	v_add_f32_e32 v98, v98, v114
	s_waitcnt lgkmcnt(2)
	v_add_f32_e32 v99, v99, v115
	s_waitcnt lgkmcnt(1)
	v_add_f32_e32 v100, v100, v116
	s_waitcnt lgkmcnt(0)
	v_add_f32_e32 v101, v101, v117
	ds_bpermute_b32 v102, v91, v68
	ds_bpermute_b32 v103, v91, v69
	ds_bpermute_b32 v104, v91, v70
	ds_bpermute_b32 v105, v91, v71
	ds_bpermute_b32 v106, v91, v72
	ds_bpermute_b32 v107, v91, v73
	ds_bpermute_b32 v108, v91, v74
	ds_bpermute_b32 v109, v91, v75
	ds_bpermute_b32 v110, v91, v94
	ds_bpermute_b32 v111, v91, v95
	ds_bpermute_b32 v112, v91, v96
	ds_bpermute_b32 v113, v91, v97
	ds_bpermute_b32 v114, v91, v98
	ds_bpermute_b32 v115, v91, v99
	ds_bpermute_b32 v116, v91, v100
	ds_bpermute_b32 v117, v91, v101
	s_waitcnt lgkmcnt(15)
	v_add_f32_e32 v68, v68, v102
	s_waitcnt lgkmcnt(14)
	v_add_f32_e32 v69, v69, v103
	s_waitcnt lgkmcnt(13)
	v_add_f32_e32 v70, v70, v104
	s_waitcnt lgkmcnt(12)
	v_add_f32_e32 v71, v71, v105
	s_waitcnt lgkmcnt(11)
	v_add_f32_e32 v72, v72, v106
	s_waitcnt lgkmcnt(10)
	v_add_f32_e32 v73, v73, v107
	s_waitcnt lgkmcnt(9)
	v_add_f32_e32 v74, v74, v108
	s_waitcnt lgkmcnt(8)
	v_add_f32_e32 v75, v75, v109
	s_waitcnt lgkmcnt(7)
	v_add_f32_e32 v94, v94, v110
	s_waitcnt lgkmcnt(6)
	v_add_f32_e32 v95, v95, v111
	s_waitcnt lgkmcnt(5)
	v_add_f32_e32 v96, v96, v112
	s_waitcnt lgkmcnt(4)
	v_add_f32_e32 v97, v97, v113
	s_waitcnt lgkmcnt(3)
	v_add_f32_e32 v98, v98, v114
	s_waitcnt lgkmcnt(2)
	v_add_f32_e32 v99, v99, v115
	s_waitcnt lgkmcnt(1)
	v_add_f32_e32 v100, v100, v116
	s_waitcnt lgkmcnt(0)
	v_add_f32_e32 v101, v101, v117
	ds_bpermute_b32 v102, v92, v68
	ds_bpermute_b32 v103, v92, v69
	ds_bpermute_b32 v104, v92, v70
	ds_bpermute_b32 v105, v92, v71
	ds_bpermute_b32 v106, v92, v72
	ds_bpermute_b32 v107, v92, v73
	ds_bpermute_b32 v108, v92, v74
	ds_bpermute_b32 v109, v92, v75
	ds_bpermute_b32 v110, v92, v94
	ds_bpermute_b32 v111, v92, v95
	ds_bpermute_b32 v112, v92, v96
	ds_bpermute_b32 v113, v92, v97
	ds_bpermute_b32 v114, v92, v98
	ds_bpermute_b32 v115, v92, v99
	ds_bpermute_b32 v116, v92, v100
	ds_bpermute_b32 v117, v92, v101
	s_waitcnt lgkmcnt(15)
	v_add_f32_e32 v68, v68, v102
	s_waitcnt lgkmcnt(14)
	v_add_f32_e32 v69, v69, v103
	s_waitcnt lgkmcnt(13)
	v_add_f32_e32 v70, v70, v104
	s_waitcnt lgkmcnt(12)
	v_add_f32_e32 v71, v71, v105
	s_waitcnt lgkmcnt(11)
	v_add_f32_e32 v72, v72, v106
	s_waitcnt lgkmcnt(10)
	v_add_f32_e32 v73, v73, v107
	s_waitcnt lgkmcnt(9)
	v_add_f32_e32 v74, v74, v108
	s_waitcnt lgkmcnt(8)
	v_add_f32_e32 v75, v75, v109
	s_waitcnt lgkmcnt(7)
	v_add_f32_e32 v94, v94, v110
	s_waitcnt lgkmcnt(6)
	v_add_f32_e32 v95, v95, v111
	s_waitcnt lgkmcnt(5)
	v_add_f32_e32 v96, v96, v112
	s_waitcnt lgkmcnt(4)
	v_add_f32_e32 v97, v97, v113
	s_waitcnt lgkmcnt(3)
	v_add_f32_e32 v98, v98, v114
	s_waitcnt lgkmcnt(2)
	v_add_f32_e32 v99, v99, v115
	s_waitcnt lgkmcnt(1)
	v_add_f32_e32 v100, v100, v116
	s_waitcnt lgkmcnt(0)
	v_add_f32_e32 v101, v101, v117
	s_mov_b64 exec, 1
	ds_write_b128 v84, v[68:71]
	ds_write_b128 v84, v[72:75] offset:16
	ds_write_b128 v84, v[94:97] offset:32
	ds_write_b128 v84, v[98:101] offset:48
	s_mov_b64 exec, -1
	s_waitcnt lgkmcnt(0)
	s_barrier
	ds_read_b32 v102, v85
	ds_read_b32 v103, v85 offset:64
	ds_read_b32 v104, v85 offset:128
	ds_read_b32 v105, v85 offset:192
	ds_read_b32 v106, v85 offset:256
	ds_read_b32 v107, v85 offset:320
	ds_read_b32 v108, v85 offset:384
	ds_read_b32 v109, v85 offset:448
	s_waitcnt lgkmcnt(0)
	v_add_f32_e32 v102, v102, v103
	v_add_f32_e32 v104, v104, v105
	v_add_f32_e32 v106, v106, v107
	v_add_f32_e32 v108, v108, v109
	v_add_f32_e32 v102, v102, v104
	v_add_f32_e32 v106, v106, v108
	v_add_f32_e32 v102, v102, v106
	v_fmamk_f32 v102, v102, 0x3a000000, v173
	v_cmp_gt_f32_e32 vcc, s33, v102
	v_mul_f32_e32 v116, 0x4f800000, v102
	s_nop 1
	v_cndmask_b32_e32 v102, v102, v116, vcc
	v_sqrt_f32_e32 v116, v102
	s_nop 1
	v_add_u32_e32 v111, -1, v116
	v_fma_f32 v112, -v111, v116, v102
	v_cmp_ge_f32_e64 s[14:15], 0, v112
	v_add_u32_e32 v112, 1, v116
	s_nop 1
	v_cndmask_b32_e64 v111, v116, v111, s[14:15]
	v_fma_f32 v116, -v112, v116, v102
	v_cmp_lt_f32_e64 s[14:15], 0, v116
	s_nop 1
	v_cndmask_b32_e64 v116, v111, v112, s[14:15]
	v_mul_f32_e32 v111, 0x37800000, v116
	v_cndmask_b32_e32 v116, v116, v111, vcc
	v_cmp_class_f32_e32 vcc, v102, v174
	s_nop 1
	v_cndmask_b32_e32 v102, v116, v102, vcc
	v_div_scale_f32 v116, s[16:17], v102, v102, 1.0
	v_rcp_f32_e32 v111, v116
	s_nop 0
	v_fma_f32 v112, -v116, v111, 1.0
	v_fmac_f32_e32 v111, v112, v111
	v_div_scale_f32 v112, vcc, 1.0, v102, 1.0
	v_mul_f32_e32 v113, v112, v111
	v_fma_f32 v114, -v116, v113, v112
	v_fmac_f32_e32 v113, v114, v111
	v_fma_f32 v116, -v116, v113, v112
	v_div_fmas_f32 v116, v116, v111, v113
	v_div_fixup_f32 v116, v116, v102, 1.0
	s_waitcnt vmcnt(0)
	v_pk_add_f32 v[118:119], v[118:119], 1.0 op_sel_hi:[1,0]
	v_pk_add_f32 v[120:121], v[120:121], 1.0 op_sel_hi:[1,0]
	v_pk_mul_f32 v[104:105], v[0:1], v[118:119]
	v_pk_mul_f32 v[106:107], v[2:3], v[120:121]
	s_ashr_i32 s9, s8, 31
	s_lshl_b64 s[6:7], s[8:9], 12
	v_readlane_b32 s0, v116, 0
	v_readlane_b32 s1, v116, 1
	v_readlane_b32 s9, v116, 2
	v_readlane_b32 s10, v116, 3
	v_readlane_b32 s11, v116, 4
	v_readlane_b32 s12, v116, 5
	v_readlane_b32 s13, v116, 6
	v_readlane_b32 s14, v116, 7
	s_nop 1
	v_mul_f32_e32 v4, s0, v4
	v_mul_f32_e32 v5, s0, v5
	v_mul_f32_e32 v6, s0, v6
	v_mul_f32_e32 v7, s0, v7
	v_pk_fma_f32 v[4:5], v[104:105], v[4:5], v[250:251]
	v_pk_fma_f32 v[6:7], v[106:107], v[6:7], v[252:253]
	v_cvt_pk_bf16_f32 v4, v4, v5
	v_cvt_pk_bf16_f32 v5, v6, v7
	v_lshl_add_u64 v[108:109], v[78:79], 0, s[6:7]
	global_store_dwordx2 v[108:109], v[4:5], off
	s_add_u32 s6, s6, 0x1000
	s_addc_u32 s7, s7, 0
	v_mul_f32_e32 v8, s1, v8
	v_mul_f32_e32 v9, s1, v9
	v_mul_f32_e32 v10, s1, v10
	v_mul_f32_e32 v11, s1, v11
	v_pk_fma_f32 v[8:9], v[104:105], v[8:9], v[250:251]
	v_pk_fma_f32 v[10:11], v[106:107], v[10:11], v[252:253]
	v_cvt_pk_bf16_f32 v8, v8, v9
	v_cvt_pk_bf16_f32 v9, v10, v11
	v_lshl_add_u64 v[108:109], v[78:79], 0, s[6:7]
	global_store_dwordx2 v[108:109], v[8:9], off
	s_add_u32 s6, s6, 0x1000
	s_addc_u32 s7, s7, 0
	v_mul_f32_e32 v12, s9, v12
	v_mul_f32_e32 v13, s9, v13
	v_mul_f32_e32 v14, s9, v14
	v_mul_f32_e32 v15, s9, v15
	v_pk_fma_f32 v[12:13], v[104:105], v[12:13], v[250:251]
	v_pk_fma_f32 v[14:15], v[106:107], v[14:15], v[252:253]
	v_cvt_pk_bf16_f32 v12, v12, v13
	v_cvt_pk_bf16_f32 v13, v14, v15
	v_lshl_add_u64 v[108:109], v[78:79], 0, s[6:7]
	global_store_dwordx2 v[108:109], v[12:13], off
	s_add_u32 s6, s6, 0x1000
	s_addc_u32 s7, s7, 0
	v_mul_f32_e32 v16, s10, v16
	v_mul_f32_e32 v17, s10, v17
	v_mul_f32_e32 v18, s10, v18
	v_mul_f32_e32 v19, s10, v19
	v_pk_fma_f32 v[16:17], v[104:105], v[16:17], v[250:251]
	v_pk_fma_f32 v[18:19], v[106:107], v[18:19], v[252:253]
	v_cvt_pk_bf16_f32 v16, v16, v17
	v_cvt_pk_bf16_f32 v17, v18, v19
	v_lshl_add_u64 v[108:109], v[78:79], 0, s[6:7]
	global_store_dwordx2 v[108:109], v[16:17], off
	s_add_u32 s6, s6, 0x1000
	s_addc_u32 s7, s7, 0
	v_mul_f32_e32 v20, s11, v20
	v_mul_f32_e32 v21, s11, v21
	v_mul_f32_e32 v22, s11, v22
	v_mul_f32_e32 v23, s11, v23
	v_pk_fma_f32 v[20:21], v[104:105], v[20:21], v[250:251]
	v_pk_fma_f32 v[22:23], v[106:107], v[22:23], v[252:253]
	v_cvt_pk_bf16_f32 v20, v20, v21
	v_cvt_pk_bf16_f32 v21, v22, v23
	v_lshl_add_u64 v[108:109], v[78:79], 0, s[6:7]
	global_store_dwordx2 v[108:109], v[20:21], off
	s_add_u32 s6, s6, 0x1000
	s_addc_u32 s7, s7, 0
	v_mul_f32_e32 v24, s12, v24
	v_mul_f32_e32 v25, s12, v25
	v_mul_f32_e32 v26, s12, v26
	v_mul_f32_e32 v27, s12, v27
	v_pk_fma_f32 v[24:25], v[104:105], v[24:25], v[250:251]
	v_pk_fma_f32 v[26:27], v[106:107], v[26:27], v[252:253]
	v_cvt_pk_bf16_f32 v24, v24, v25
	v_cvt_pk_bf16_f32 v25, v26, v27
	v_lshl_add_u64 v[108:109], v[78:79], 0, s[6:7]
	global_store_dwordx2 v[108:109], v[24:25], off
	s_add_u32 s6, s6, 0x1000
	s_addc_u32 s7, s7, 0
	v_mul_f32_e32 v28, s13, v28
	v_mul_f32_e32 v29, s13, v29
	v_mul_f32_e32 v30, s13, v30
	v_mul_f32_e32 v31, s13, v31
	v_pk_fma_f32 v[28:29], v[104:105], v[28:29], v[250:251]
	v_pk_fma_f32 v[30:31], v[106:107], v[30:31], v[252:253]
	v_cvt_pk_bf16_f32 v28, v28, v29
	v_cvt_pk_bf16_f32 v29, v30, v31
	v_lshl_add_u64 v[108:109], v[78:79], 0, s[6:7]
	global_store_dwordx2 v[108:109], v[28:29], off
	s_add_u32 s6, s6, 0x1000
	s_addc_u32 s7, s7, 0
	v_mul_f32_e32 v32, s14, v32
	v_mul_f32_e32 v33, s14, v33
	v_mul_f32_e32 v34, s14, v34
	v_mul_f32_e32 v35, s14, v35
	v_pk_fma_f32 v[32:33], v[104:105], v[32:33], v[250:251]
	v_pk_fma_f32 v[34:35], v[106:107], v[34:35], v[252:253]
	v_cvt_pk_bf16_f32 v32, v32, v33
	v_cvt_pk_bf16_f32 v33, v34, v35
	v_lshl_add_u64 v[108:109], v[78:79], 0, s[6:7]
	global_store_dwordx2 v[108:109], v[32:33], off
	s_add_u32 s6, s6, 0x1000
	s_addc_u32 s7, s7, 0
	v_readlane_b32 s0, v116, 8
	v_readlane_b32 s1, v116, 9
	v_readlane_b32 s9, v116, 10
	v_readlane_b32 s10, v116, 11
	v_readlane_b32 s11, v116, 12
	v_readlane_b32 s12, v116, 13
	v_readlane_b32 s13, v116, 14
	v_readlane_b32 s14, v116, 15
	s_nop 1
	v_mul_f32_e32 v36, s0, v36
	v_mul_f32_e32 v37, s0, v37
	v_mul_f32_e32 v38, s0, v38
	v_mul_f32_e32 v39, s0, v39
	v_pk_fma_f32 v[36:37], v[104:105], v[36:37], v[250:251]
	v_pk_fma_f32 v[38:39], v[106:107], v[38:39], v[252:253]
	v_cvt_pk_bf16_f32 v36, v36, v37
	v_cvt_pk_bf16_f32 v37, v38, v39
	v_lshl_add_u64 v[108:109], v[78:79], 0, s[6:7]
	global_store_dwordx2 v[108:109], v[36:37], off
	s_add_u32 s6, s6, 0x1000
	s_addc_u32 s7, s7, 0
	v_mul_f32_e32 v40, s1, v40
	v_mul_f32_e32 v41, s1, v41
	v_mul_f32_e32 v42, s1, v42
	v_mul_f32_e32 v43, s1, v43
	v_pk_fma_f32 v[40:41], v[104:105], v[40:41], v[250:251]
	v_pk_fma_f32 v[42:43], v[106:107], v[42:43], v[252:253]
	v_cvt_pk_bf16_f32 v40, v40, v41
	v_cvt_pk_bf16_f32 v41, v42, v43
	v_lshl_add_u64 v[108:109], v[78:79], 0, s[6:7]
	global_store_dwordx2 v[108:109], v[40:41], off
	s_add_u32 s6, s6, 0x1000
	s_addc_u32 s7, s7, 0
	v_mul_f32_e32 v44, s9, v44
	v_mul_f32_e32 v45, s9, v45
	v_mul_f32_e32 v46, s9, v46
	v_mul_f32_e32 v47, s9, v47
	v_pk_fma_f32 v[44:45], v[104:105], v[44:45], v[250:251]
	v_pk_fma_f32 v[46:47], v[106:107], v[46:47], v[252:253]
	v_cvt_pk_bf16_f32 v44, v44, v45
	v_cvt_pk_bf16_f32 v45, v46, v47
	v_lshl_add_u64 v[108:109], v[78:79], 0, s[6:7]
	global_store_dwordx2 v[108:109], v[44:45], off
	s_add_u32 s6, s6, 0x1000
	s_addc_u32 s7, s7, 0
	v_mul_f32_e32 v48, s10, v48
	v_mul_f32_e32 v49, s10, v49
	v_mul_f32_e32 v50, s10, v50
	v_mul_f32_e32 v51, s10, v51
	v_pk_fma_f32 v[48:49], v[104:105], v[48:49], v[250:251]
	v_pk_fma_f32 v[50:51], v[106:107], v[50:51], v[252:253]
	v_cvt_pk_bf16_f32 v48, v48, v49
	v_cvt_pk_bf16_f32 v49, v50, v51
	v_lshl_add_u64 v[108:109], v[78:79], 0, s[6:7]
	global_store_dwordx2 v[108:109], v[48:49], off
	s_add_u32 s6, s6, 0x1000
	s_addc_u32 s7, s7, 0
	v_mul_f32_e32 v52, s11, v52
	v_mul_f32_e32 v53, s11, v53
	v_mul_f32_e32 v54, s11, v54
	v_mul_f32_e32 v55, s11, v55
	v_pk_fma_f32 v[52:53], v[104:105], v[52:53], v[250:251]
	v_pk_fma_f32 v[54:55], v[106:107], v[54:55], v[252:253]
	v_cvt_pk_bf16_f32 v52, v52, v53
	v_cvt_pk_bf16_f32 v53, v54, v55
	v_lshl_add_u64 v[108:109], v[78:79], 0, s[6:7]
	global_store_dwordx2 v[108:109], v[52:53], off
	s_add_u32 s6, s6, 0x1000
	s_addc_u32 s7, s7, 0
	v_mul_f32_e32 v56, s12, v56
	v_mul_f32_e32 v57, s12, v57
	v_mul_f32_e32 v58, s12, v58
	v_mul_f32_e32 v59, s12, v59
	v_pk_fma_f32 v[56:57], v[104:105], v[56:57], v[250:251]
	v_pk_fma_f32 v[58:59], v[106:107], v[58:59], v[252:253]
	v_cvt_pk_bf16_f32 v56, v56, v57
	v_cvt_pk_bf16_f32 v57, v58, v59
	v_lshl_add_u64 v[108:109], v[78:79], 0, s[6:7]
	global_store_dwordx2 v[108:109], v[56:57], off
	s_add_u32 s6, s6, 0x1000
	s_addc_u32 s7, s7, 0
	v_mul_f32_e32 v60, s13, v60
	v_mul_f32_e32 v61, s13, v61
	v_mul_f32_e32 v62, s13, v62
	v_mul_f32_e32 v63, s13, v63
	v_pk_fma_f32 v[60:61], v[104:105], v[60:61], v[250:251]
	v_pk_fma_f32 v[62:63], v[106:107], v[62:63], v[252:253]
	v_cvt_pk_bf16_f32 v60, v60, v61
	v_cvt_pk_bf16_f32 v61, v62, v63
	v_lshl_add_u64 v[108:109], v[78:79], 0, s[6:7]
	global_store_dwordx2 v[108:109], v[60:61], off
	s_add_u32 s6, s6, 0x1000
	s_addc_u32 s7, s7, 0
	v_mul_f32_e32 v64, s14, v64
	v_mul_f32_e32 v65, s14, v65
	v_mul_f32_e32 v66, s14, v66
	v_mul_f32_e32 v67, s14, v67
	v_pk_fma_f32 v[64:65], v[104:105], v[64:65], v[250:251]
	v_pk_fma_f32 v[66:67], v[106:107], v[66:67], v[252:253]
	v_cvt_pk_bf16_f32 v64, v64, v65
	v_cvt_pk_bf16_f32 v65, v66, v67
	v_lshl_add_u64 v[108:109], v[78:79], 0, s[6:7]
	global_store_dwordx2 v[108:109], v[64:65], off
	s_add_u32 s6, s6, 0x1000
	s_addc_u32 s7, s7, 0
	s_mov_b32 s12, 0x8000
	s_mov_b32 s13, 0
	s_waitcnt lgkmcnt(0)
	s_barrier
	s_add_i32 s20, s20, s34
	s_add_i32 s8, s8, s88
	s_cmpk_gt_i32 s20, 0x3ff
	s_cbranch_scc0 .Lnm_n2_loop
	s_branch .LBB0_1048
